# type-B attention loop: row-sum adds of tile t issued between the QK MFMAs of tile t+1 (S double-buffered), loads always issued with counted vmcnt(2)
# speedup vs baseline: 1.0569x; 1.0029x over previous
.LBB0_184:
	s_lshl_b32 s2, s64, 2
	s_add_i32 s2, s2, s33
	s_mul_i32 s40, s2, 0x108000
	s_mul_hi_i32 s41, s2, 0x108000
	s_add_u32 s12, s77, s40
	s_addc_u32 s13, s71, s41
	s_add_u32 s22, s72, s40
	v_ashrrev_i32_e32 v0, 31, v148
	s_addc_u32 s23, s66, s41
	v_lshrrev_b32_e32 v0, 29, v0
	s_add_u32 s14, s24, s40
	v_add_u32_e32 v0, v148, v0
	s_addc_u32 s15, s76, s41
	v_ashrrev_i32_e32 v26, 3, v0
	v_and_b32_e32 v0, -8, v0
	s_and_b64 s[2:3], s[88:89], exec
	v_sub_u32_e32 v27, v148, v0
	v_lshlrev_b32_e32 v0, 6, v26
	s_cselect_b32 s3, 0, 0x2000
	v_lshl_add_u32 v2, v27, 3, v0
	v_mov_b64_e32 v[4:5], s[14:15]
	v_lshlrev_b32_e32 v0, 4, v148
	s_cselect_b32 s2, 0x84, 4
	v_mad_i64_i32 v[4:5], s[14:15], v156, s54, v[4:5]
	v_and_b32_e32 v18, 0x70, v0
	v_mov_b32_e32 v19, v1
	s_lshl_b32 s38, s3, 7
	v_lshl_add_u64 v[4:5], v[4:5], 0, v[18:19]
	s_add_u32 s14, s22, s38
	v_ashrrev_i32_e32 v3, 31, v2
	v_lshrrev_b32_e32 v6, 1, v148
	v_and_b32_e32 v19, 31, v148
	s_addc_u32 s15, s23, 0
	v_lshlrev_b64 v[20:21], 1, v[2:3]
	v_and_or_b32 v0, v6, s5, v19
	v_lshl_add_u64 v[2:3], s[14:15], 0, v[20:21]
	s_lshl_b32 s96, s3, 1
	v_and_b32_e32 v22, 0xffffffe0, v156
	v_add_lshl_u32 v0, v0, s65, 7
	v_lshl_add_u64 v[4:5], v[4:5], 0, s[96:97]
	global_load_dwordx4 v[66:69], v[2:3], off
	global_load_dwordx4 v[78:81], v[4:5], off
	v_lshl_add_u64 v[2:3], s[12:13], 0, v[0:1]
	v_ashrrev_i32_e32 v23, 31, v22
	s_or_b32 s3, s38, 0x2000
	v_lshl_add_u64 v[2:3], v[22:23], 1, v[2:3]
	v_and_b32_e32 v0, 16, v6
	s_add_u32 s12, s22, s3
	v_lshl_add_u64 v[2:3], v[2:3], 0, v[0:1]
	s_addc_u32 s13, s23, 0
	global_load_dwordx4 v[70:73], v[2:3], off
	global_load_dwordx4 v[74:77], v[2:3], off offset:32
	v_lshl_add_u64 v[2:3], s[12:13], 0, v[20:21]
	global_load_dwordx4 v[86:89], v[4:5], off offset:128
	global_load_dwordx4 v[82:85], v[2:3], off
	v_mad_i64_i32 v[24:25], s[12:13], v156, s54, 0
	v_mad_u64_u32 v[122:123], s[12:13], v156, s4, v[18:19]
	s_add_u32 s12, s36, s96
	v_or_b32_e32 v24, v24, v18
	s_addc_u32 s13, s37, 0
	v_cmp_lt_i32_e32 vcc, v207, v206
	s_waitcnt vmcnt(14)
	v_lshl_add_u64 v[124:125], s[12:13], 0, v[24:25]
	s_add_u32 s12, s36, s38
	v_cndmask_b32_e32 v23, v205, v207, vcc
	v_mul_u32_u24_e32 v133, 0x90, v19
	v_mul_lo_u32 v18, v26, s4
	v_lshl_or_b32 v34, v22, 1, v0
	s_addc_u32 s13, s37, 0
	s_mov_b32 s3, 3
	v_mov_b32_e32 v2, v1
	v_mov_b32_e32 v3, v1
	v_mov_b32_e32 v4, v1
	v_mov_b32_e32 v5, v1
	v_mov_b32_e32 v6, v1
	v_mov_b32_e32 v7, v1
	v_mov_b32_e32 v8, v1
	v_mov_b32_e32 v9, v1
	v_mov_b32_e32 v10, v1
	v_mov_b32_e32 v11, v1
	v_mov_b32_e32 v12, v1
	v_mov_b32_e32 v13, v1
	v_mov_b32_e32 v14, v1
	v_mov_b32_e32 v15, v1
	v_mov_b32_e32 v16, v1
	v_mov_b32_e32 v17, v1
	v_lshlrev_b32_e32 v132, 2, v23
	v_lshl_add_u32 v123, v27, 4, v18
	v_lshl_add_u64 v[126:127], s[12:13], 0, v[20:21]
	v_mov_b32_e32 v18, v1
	v_mov_b32_e32 v19, v1
	v_mov_b32_e32 v20, v1
	v_mov_b32_e32 v21, v1
	v_mov_b32_e32 v22, v1
	v_mov_b32_e32 v23, v1
	v_mov_b32_e32 v24, v1
	v_mov_b32_e32 v25, v1
	v_mov_b32_e32 v26, v1
	v_mov_b32_e32 v27, v1
	v_mov_b32_e32 v28, v1
	v_mov_b32_e32 v29, v1
	v_mov_b32_e32 v30, v1
	v_mov_b32_e32 v31, v1
	v_mov_b32_e32 v32, v1
	v_mov_b32_e32 v33, v1
	v_mov_b32_e32 v134, 0
	v_bfrev_b32_e32 v218, 1
	v_mov_b32_e32 v219, v218
	v_mov_b32_e32 v220, v218
	v_mov_b32_e32 v221, v218
	v_mov_b32_e32 v222, v218
	v_mov_b32_e32 v223, v218
	v_mov_b32_e32 v224, v218
	v_mov_b32_e32 v225, v218
	v_mov_b32_e32 v226, v218
	v_mov_b32_e32 v227, v218
	v_mov_b32_e32 v228, v218
	v_mov_b32_e32 v229, v218
	v_mov_b32_e32 v230, v218
	v_mov_b32_e32 v231, v218
	v_mov_b32_e32 v232, v218
	v_mov_b32_e32 v233, v218
	v_add_u32_e32 v135, v133, v34
	v_mov_b32_e32 v136, 0
	s_waitcnt vmcnt(5)
	ds_write_b128 v123, v[66:69]
	s_waitcnt vmcnt(4)
	ds_write_b128 v122, v[78:81] offset:9216
	s_waitcnt lgkmcnt(0)
	s_barrier
	s_cmp_lg_u32 s98, 0
	s_cbranch_scc1 .LBB0_186_sl
	v_lshl_add_u64 v[238:239], v[126:127], 0, s[40:41]
	v_lshl_add_u64 v[242:243], v[124:125], 0, s[40:41]
	s_mov_b32 s12, 0x6e73800
	s_mov_b32 s13, 0
	v_lshl_add_u64 v[240:241], v[238:239], 0, s[12:13]
	s_mov_b32 s12, 0x6e71800
	v_lshl_add_u64 v[238:239], v[238:239], 0, s[12:13]
	s_mov_b32 s12, 0x76ad900
	v_lshl_add_u64 v[242:243], v[242:243], 0, s[12:13]
	s_waitcnt vmcnt(2)
	v_add_u32_e32 v190, v133, v0
	v_mov_b32_e32 v158, 0
	v_mov_b32_e32 v159, 0
	v_mov_b32_e32 v160, 0
	v_mov_b32_e32 v161, 0
	v_mov_b32_e32 v162, 0
	v_mov_b32_e32 v163, 0
	v_mov_b32_e32 v164, 0
	v_mov_b32_e32 v165, 0
	v_mov_b32_e32 v166, 0
	v_mov_b32_e32 v167, 0
	v_mov_b32_e32 v168, 0
	v_mov_b32_e32 v169, 0
	v_mov_b32_e32 v170, 0
	v_mov_b32_e32 v171, 0
	v_mov_b32_e32 v172, 0
	v_mov_b32_e32 v173, 0
	v_mov_b32_e32 v174, 0
	v_mov_b32_e32 v175, 0
	v_mov_b32_e32 v176, 0
	v_mov_b32_e32 v177, 0
	v_mov_b32_e32 v178, 0
	v_mov_b32_e32 v179, 0
	v_mov_b32_e32 v180, 0
	v_mov_b32_e32 v181, 0
	v_mov_b32_e32 v182, 0
	v_mov_b32_e32 v183, 0
	v_mov_b32_e32 v184, 0
	v_mov_b32_e32 v185, 0
	v_mov_b32_e32 v186, 0
	v_mov_b32_e32 v187, 0
	v_mov_b32_e32 v188, 0
	v_mov_b32_e32 v189, 0
	s_mov_b32 s3, 0
.Lb2_loop:
	global_load_dwordx4 v[66:69], v[238:239], off
	global_load_dwordx4 v[78:81], v[242:243], off
	ds_read_b128 v[90:93], v135
	ds_read_b128 v[94:97], v135 offset:32
	ds_read_b128 v[98:101], v135 offset:4608
	ds_read_b128 v[138:141], v135 offset:4640
	s_waitcnt lgkmcnt(3)
	s_nop 0
	v_mfma_f32_32x32x16_bf16 v[50:65], v[90:93], v[70:73], v[218:233]
	v_add_f32_e32 v234, v158, v159
	v_add_f32_e32 v235, v174, v175
	v_add_f32_e32 v234, v160, v234
	v_add_f32_e32 v235, v176, v235
	v_add_f32_e32 v234, v161, v234
	v_add_f32_e32 v235, v177, v235
	v_add_f32_e32 v234, v162, v234
	v_add_f32_e32 v235, v178, v235
	s_waitcnt lgkmcnt(1)
	v_mfma_f32_32x32x16_bf16 v[34:49], v[98:101], v[70:73], v[218:233]
	v_add_f32_e32 v234, v163, v234
	v_add_f32_e32 v235, v179, v235
	v_add_f32_e32 v234, v164, v234
	v_add_f32_e32 v235, v180, v235
	v_add_f32_e32 v234, v165, v234
	v_add_f32_e32 v235, v181, v235
	v_add_f32_e32 v234, v166, v234
	v_add_f32_e32 v235, v182, v235
	v_mfma_f32_32x32x16_bf16 v[50:65], v[94:97], v[74:77], v[50:65]
	ds_read_b128 v[118:121], v190 offset:9216
	ds_read_b128 v[114:117], v190 offset:9248
	ds_read_b128 v[110:113], v190 offset:9280
	ds_read_b128 v[106:109], v190 offset:9312
	ds_read_b128 v[102:105], v190 offset:13824
	ds_read_b128 v[98:101], v190 offset:13856
	ds_read_b128 v[90:93], v190 offset:13888
	ds_read_b128 v[94:97], v190 offset:13920
	v_add_f32_e32 v234, v167, v234
	v_add_f32_e32 v235, v183, v235
	v_add_f32_e32 v234, v168, v234
	v_add_f32_e32 v235, v184, v235
	v_add_f32_e32 v234, v169, v234
	v_add_f32_e32 v235, v185, v235
	v_add_f32_e32 v234, v170, v234
	v_add_f32_e32 v235, v186, v235
	s_waitcnt lgkmcnt(8)
	v_mfma_f32_32x32x16_bf16 v[34:49], v[138:141], v[74:77], v[34:49]
	v_add_f32_e32 v234, v171, v234
	v_add_f32_e32 v235, v187, v235
	v_add_f32_e32 v234, v172, v234
	v_add_f32_e32 v235, v188, v235
	v_add_f32_e32 v234, v173, v234
	v_add_f32_e32 v235, v189, v235
	v_add_f32_e32 v234, v235, v234
	v_add_f32_e32 v136, v136, v234
	s_cmp_eq_u32 s3, 0
	s_cbranch_scc0 .Lb2_nofirst
	s_nop 15
	v_max3_f32 v234, v50, v51, v52
	v_max3_f32 v235, v34, v35, v36
	v_max3_f32 v234, v234, v53, v54
	v_max3_f32 v234, v234, v55, v56
	v_max3_f32 v234, v234, v57, v58
	v_max3_f32 v234, v234, v59, v60
	v_max3_f32 v234, v234, v61, v62
	v_max3_f32 v234, v234, v63, v64
	v_max3_f32 v235, v235, v37, v38
	v_max3_f32 v235, v235, v39, v40
	v_max3_f32 v235, v235, v41, v42
	v_max3_f32 v235, v235, v43, v44
	v_max3_f32 v235, v235, v45, v46
	v_max3_f32 v235, v235, v47, v48
	v_max3_f32 v234, v234, v65, v49
	v_max_f32_e32 v234, v234, v235
	ds_bpermute_b32 v235, v132, v234
	s_waitcnt lgkmcnt(0)
	v_max_f32_e32 v234, v234, v235
	v_add_f32_e32 v134, v134, v234
	v_xor_b32_e32 v218, 0x80000000, v234
	v_mov_b32_e32 v219, v218
	v_mov_b32_e32 v220, v218
	v_mov_b32_e32 v221, v218
	v_mov_b32_e32 v222, v218
	v_mov_b32_e32 v223, v218
	v_mov_b32_e32 v224, v218
	v_mov_b32_e32 v225, v218
	v_mov_b32_e32 v226, v218
	v_mov_b32_e32 v227, v218
	v_mov_b32_e32 v228, v218
	v_mov_b32_e32 v229, v218
	v_mov_b32_e32 v230, v218
	v_mov_b32_e32 v231, v218
	v_mov_b32_e32 v232, v218
	v_mov_b32_e32 v233, v218
	v_sub_f32_e32 v50, v50, v234
	v_sub_f32_e32 v51, v51, v234
	v_sub_f32_e32 v52, v52, v234
	v_sub_f32_e32 v53, v53, v234
	v_sub_f32_e32 v54, v54, v234
	v_sub_f32_e32 v55, v55, v234
	v_sub_f32_e32 v56, v56, v234
	v_sub_f32_e32 v57, v57, v234
	v_sub_f32_e32 v58, v58, v234
	v_sub_f32_e32 v59, v59, v234
	v_sub_f32_e32 v60, v60, v234
	v_sub_f32_e32 v61, v61, v234
	v_sub_f32_e32 v62, v62, v234
	v_sub_f32_e32 v63, v63, v234
	v_sub_f32_e32 v64, v64, v234
	v_sub_f32_e32 v65, v65, v234
	v_sub_f32_e32 v34, v34, v234
	v_sub_f32_e32 v35, v35, v234
	v_sub_f32_e32 v36, v36, v234
	v_sub_f32_e32 v37, v37, v234
	v_sub_f32_e32 v38, v38, v234
	v_sub_f32_e32 v39, v39, v234
	v_sub_f32_e32 v40, v40, v234
	v_sub_f32_e32 v41, v41, v234
	v_sub_f32_e32 v42, v42, v234
	v_sub_f32_e32 v43, v43, v234
	v_sub_f32_e32 v44, v44, v234
	v_sub_f32_e32 v45, v45, v234
	v_sub_f32_e32 v46, v46, v234
	v_sub_f32_e32 v47, v47, v234
	v_sub_f32_e32 v48, v48, v234
	v_sub_f32_e32 v49, v49, v234
.Lb2_nofirst:
	v_exp_f32_e32 v50, v50
	v_exp_f32_e32 v51, v51
	v_exp_f32_e32 v52, v52
	v_exp_f32_e32 v53, v53
	v_exp_f32_e32 v54, v54
	v_exp_f32_e32 v55, v55
	v_exp_f32_e32 v56, v56
	v_exp_f32_e32 v57, v57
	v_cvt_pk_bf16_f32 v138, v50, v51
	v_cvt_pk_bf16_f32 v139, v52, v53
	v_cvt_pk_bf16_f32 v140, v54, v55
	v_cvt_pk_bf16_f32 v141, v56, v57
	v_exp_f32_e32 v58, v58
	v_exp_f32_e32 v59, v59
	s_waitcnt lgkmcnt(0)
	v_mfma_f32_32x32x16_bf16 v[2:17], v[118:121], v[138:141], v[2:17]
	v_exp_f32_e32 v60, v60
	v_exp_f32_e32 v61, v61
	v_exp_f32_e32 v62, v62
	v_exp_f32_e32 v63, v63
	v_exp_f32_e32 v64, v64
	v_exp_f32_e32 v65, v65
	v_cvt_pk_bf16_f32 v142, v58, v59
	v_mfma_f32_32x32x16_bf16 v[18:33], v[102:105], v[138:141], v[18:33]
	v_cvt_pk_bf16_f32 v143, v60, v61
	v_cvt_pk_bf16_f32 v144, v62, v63
	v_cvt_pk_bf16_f32 v145, v64, v65
	v_exp_f32_e32 v34, v34
	v_exp_f32_e32 v35, v35
	v_exp_f32_e32 v36, v36
	v_exp_f32_e32 v37, v37
	v_mfma_f32_32x32x16_bf16 v[2:17], v[114:117], v[142:145], v[2:17]
	v_exp_f32_e32 v38, v38
	v_exp_f32_e32 v39, v39
	v_exp_f32_e32 v40, v40
	v_exp_f32_e32 v41, v41
	v_cvt_pk_bf16_f32 v150, v34, v35
	v_cvt_pk_bf16_f32 v151, v36, v37
	v_cvt_pk_bf16_f32 v152, v38, v39
	v_mfma_f32_32x32x16_bf16 v[18:33], v[98:101], v[142:145], v[18:33]
	v_cvt_pk_bf16_f32 v153, v40, v41
	v_exp_f32_e32 v42, v42
	v_exp_f32_e32 v43, v43
	v_exp_f32_e32 v44, v44
	v_exp_f32_e32 v45, v45
	v_exp_f32_e32 v46, v46
	v_exp_f32_e32 v47, v47
	v_mfma_f32_32x32x16_bf16 v[2:17], v[110:113], v[150:153], v[2:17]
	v_exp_f32_e32 v48, v48
	v_exp_f32_e32 v49, v49
	v_cvt_pk_bf16_f32 v154, v42, v43
	v_cvt_pk_bf16_f32 v155, v44, v45
	v_cvt_pk_bf16_f32 v156, v46, v47
	v_cvt_pk_bf16_f32 v157, v48, v49
	v_mfma_f32_32x32x16_bf16 v[18:33], v[90:93], v[150:153], v[18:33]
	s_waitcnt vmcnt(2)
	ds_write_b128 v123, v[82:85] offset:18432
	ds_write_b128 v122, v[86:89] offset:27648
	v_mfma_f32_32x32x16_bf16 v[2:17], v[106:109], v[154:157], v[2:17]
	v_mfma_f32_32x32x16_bf16 v[18:33], v[94:97], v[154:157], v[18:33]
	s_waitcnt lgkmcnt(0)
	s_barrier
	s_barrier
	global_load_dwordx4 v[82:85], v[240:241], off
	global_load_dwordx4 v[86:89], v[242:243], off offset:128
	ds_read_b128 v[90:93], v135 offset:18432
	ds_read_b128 v[94:97], v135 offset:18464
	ds_read_b128 v[98:101], v135 offset:23040
	ds_read_b128 v[138:141], v135 offset:23072
	s_waitcnt lgkmcnt(3)
	s_nop 0
	v_mfma_f32_32x32x16_bf16 v[158:173], v[90:93], v[70:73], v[218:233]
	v_add_f32_e32 v234, v50, v51
	v_add_f32_e32 v235, v34, v35
	v_add_f32_e32 v234, v52, v234
	v_add_f32_e32 v235, v36, v235
	v_add_f32_e32 v234, v53, v234
	v_add_f32_e32 v235, v37, v235
	v_add_f32_e32 v234, v54, v234
	v_add_f32_e32 v235, v38, v235
	s_waitcnt lgkmcnt(1)
	v_mfma_f32_32x32x16_bf16 v[174:189], v[98:101], v[70:73], v[218:233]
	v_add_f32_e32 v234, v55, v234
	v_add_f32_e32 v235, v39, v235
	v_add_f32_e32 v234, v56, v234
	v_add_f32_e32 v235, v40, v235
	v_add_f32_e32 v234, v57, v234
	v_add_f32_e32 v235, v41, v235
	v_add_f32_e32 v234, v58, v234
	v_add_f32_e32 v235, v42, v235
	v_mfma_f32_32x32x16_bf16 v[158:173], v[94:97], v[74:77], v[158:173]
	ds_read_b128 v[118:121], v190 offset:27648
	ds_read_b128 v[114:117], v190 offset:27680
	ds_read_b128 v[110:113], v190 offset:27712
	ds_read_b128 v[106:109], v190 offset:27744
	ds_read_b128 v[102:105], v190 offset:32256
	ds_read_b128 v[98:101], v190 offset:32288
	ds_read_b128 v[90:93], v190 offset:32320
	ds_read_b128 v[94:97], v190 offset:32352
	v_add_f32_e32 v234, v59, v234
	v_add_f32_e32 v235, v43, v235
	v_add_f32_e32 v234, v60, v234
	v_add_f32_e32 v235, v44, v235
	v_add_f32_e32 v234, v61, v234
	v_add_f32_e32 v235, v45, v235
	v_add_f32_e32 v234, v62, v234
	v_add_f32_e32 v235, v46, v235
	s_waitcnt lgkmcnt(8)
	v_mfma_f32_32x32x16_bf16 v[174:189], v[138:141], v[74:77], v[174:189]
	v_add_f32_e32 v234, v63, v234
	v_add_f32_e32 v235, v47, v235
	v_add_f32_e32 v234, v64, v234
	v_add_f32_e32 v235, v48, v235
	v_add_f32_e32 v234, v65, v234
	v_add_f32_e32 v235, v49, v235
	v_add_f32_e32 v234, v235, v234
	v_add_f32_e32 v136, v136, v234
	v_exp_f32_e32 v158, v158
	v_exp_f32_e32 v159, v159
	v_exp_f32_e32 v160, v160
	v_exp_f32_e32 v161, v161
	v_exp_f32_e32 v162, v162
	v_exp_f32_e32 v163, v163
	v_exp_f32_e32 v164, v164
	v_exp_f32_e32 v165, v165
	v_cvt_pk_bf16_f32 v138, v158, v159
	v_cvt_pk_bf16_f32 v139, v160, v161
	v_cvt_pk_bf16_f32 v140, v162, v163
	v_cvt_pk_bf16_f32 v141, v164, v165
	v_exp_f32_e32 v166, v166
	v_exp_f32_e32 v167, v167
	s_waitcnt lgkmcnt(0)
	v_mfma_f32_32x32x16_bf16 v[2:17], v[118:121], v[138:141], v[2:17]
	v_exp_f32_e32 v168, v168
	v_exp_f32_e32 v169, v169
	v_exp_f32_e32 v170, v170
	v_exp_f32_e32 v171, v171
	v_exp_f32_e32 v172, v172
	v_exp_f32_e32 v173, v173
	v_cvt_pk_bf16_f32 v142, v166, v167
	v_mfma_f32_32x32x16_bf16 v[18:33], v[102:105], v[138:141], v[18:33]
	v_cvt_pk_bf16_f32 v143, v168, v169
	v_cvt_pk_bf16_f32 v144, v170, v171
	v_cvt_pk_bf16_f32 v145, v172, v173
	v_exp_f32_e32 v174, v174
	v_exp_f32_e32 v175, v175
	v_exp_f32_e32 v176, v176
	v_exp_f32_e32 v177, v177
	v_mfma_f32_32x32x16_bf16 v[2:17], v[114:117], v[142:145], v[2:17]
	v_exp_f32_e32 v178, v178
	v_exp_f32_e32 v179, v179
	v_exp_f32_e32 v180, v180
	v_exp_f32_e32 v181, v181
	v_cvt_pk_bf16_f32 v150, v174, v175
	v_cvt_pk_bf16_f32 v151, v176, v177
	v_cvt_pk_bf16_f32 v152, v178, v179
	v_mfma_f32_32x32x16_bf16 v[18:33], v[98:101], v[142:145], v[18:33]
	v_cvt_pk_bf16_f32 v153, v180, v181
	v_exp_f32_e32 v182, v182
	v_exp_f32_e32 v183, v183
	v_exp_f32_e32 v184, v184
	v_exp_f32_e32 v185, v185
	v_exp_f32_e32 v186, v186
	v_exp_f32_e32 v187, v187
	v_mfma_f32_32x32x16_bf16 v[2:17], v[110:113], v[150:153], v[2:17]
	v_exp_f32_e32 v188, v188
	v_exp_f32_e32 v189, v189
	v_cvt_pk_bf16_f32 v154, v182, v183
	v_cvt_pk_bf16_f32 v155, v184, v185
	v_cvt_pk_bf16_f32 v156, v186, v187
	v_cvt_pk_bf16_f32 v157, v188, v189
	v_mfma_f32_32x32x16_bf16 v[18:33], v[90:93], v[150:153], v[18:33]
	s_waitcnt vmcnt(2)
	ds_write_b128 v123, v[66:69]
	ds_write_b128 v122, v[78:81] offset:9216
	v_mfma_f32_32x32x16_bf16 v[2:17], v[106:109], v[154:157], v[2:17]
	v_mfma_f32_32x32x16_bf16 v[18:33], v[94:97], v[154:157], v[18:33]
	s_waitcnt lgkmcnt(0)
	s_barrier
	s_barrier
	v_lshl_add_u64 v[242:243], v[242:243], 0, s[30:31]
	v_lshl_add_u64 v[238:239], v[238:239], 0, s[28:29]
	v_lshl_add_u64 v[240:241], v[240:241], 0, s[28:29]
	s_add_i32 s3, s3, 2
	s_cmp_lt_u32 s3, s2
	s_cbranch_scc1 .Lb2_loop
	v_add_f32_e32 v234, v158, v159
	v_add_f32_e32 v235, v174, v175
	v_add_f32_e32 v234, v160, v234
	v_add_f32_e32 v235, v176, v235
	v_add_f32_e32 v234, v161, v234
	v_add_f32_e32 v235, v177, v235
	v_add_f32_e32 v234, v162, v234
	v_add_f32_e32 v235, v178, v235
	v_add_f32_e32 v234, v163, v234
	v_add_f32_e32 v235, v179, v235
	v_add_f32_e32 v234, v164, v234
	v_add_f32_e32 v235, v180, v235
	v_add_f32_e32 v234, v165, v234
	v_add_f32_e32 v235, v181, v235
	v_add_f32_e32 v234, v166, v234
	v_add_f32_e32 v235, v182, v235
	v_add_f32_e32 v234, v167, v234
	v_add_f32_e32 v235, v183, v235
	v_add_f32_e32 v234, v168, v234
	v_add_f32_e32 v235, v184, v235
	v_add_f32_e32 v234, v169, v234
	v_add_f32_e32 v235, v185, v235
	v_add_f32_e32 v234, v170, v234
	v_add_f32_e32 v235, v186, v235
	v_add_f32_e32 v234, v171, v234
	v_add_f32_e32 v235, v187, v235
	v_add_f32_e32 v234, v172, v234
	v_add_f32_e32 v235, v188, v235
	v_add_f32_e32 v234, v173, v234
	v_add_f32_e32 v235, v189, v235
	v_add_f32_e32 v234, v235, v234
	v_add_f32_e32 v136, v136, v234
	s_waitcnt vmcnt(0)
	s_branch .LBB0_196
